# attention loop edge: register rotation + next-tile global loads deferred from before the loop barrier to the top of the next iteration, behind the K-fragment LDS reads
# baseline (speedup 1.0000x reference)
; __device__ __forceinline__ void unit(unsigned char* ws, LAS unsigned char* lds, int b, int h, int mp, int qb, const int tid_in) {
;     ...
;     const int sr = tid >> 3, sc = tid & 7;
;     const bf16_t* kg = K + (size_t)sr * 512 + sc * 8;
;     const int vp = tid >> 4, vc = tid & 15;
;     const bf16_t* vg = V + (size_t)(2 * vp) * 512 + vc * 8;
;     u32x4 kA = *(const u32x4*)kg, vA0 = *(const u32x4*)vg, vA1 = *(const u32x4*)(vg + 512);
;     u32x4 kB = *(const u32x4*)(kg + (size_t)64 * 512), vB0 = *(const u32x4*)(vg + (size_t)64 * 512), vB1 = *(const u32x4*)(vg + (size_t)64 * 512 + 512);
;     ...
;     FA3_STAGE(0);
;     kA = kB; vA0 = vB0; vA1 = vB1;
;     { const size_t off = (size_t)2 * 64 * 512; kB = *(const u32x4*)(kg + off); vB0 = *(const u32x4*)(vg + off); vB1 = *(const u32x4*)(vg + off + 512); }
;     __syncthreads();
.LBB0_181:
	s_or_b64 exec, exec, s[22:23]
	v_bfe_u32 v37, v2, 4, 2
	v_lshlrev_b32_e32 v0, 4, v37
	v_ashrrev_i32_e32 v18, 3, v2
	v_lshl_add_u64 v[16:17], s[18:19], 0, v[0:1]
	v_ashrrev_i32_e32 v19, 31, v18
	v_lshlrev_b32_e32 v0, 3, v2
	v_lshlrev_b64 v[20:21], 10, v[18:19]
	v_and_b32_e32 v0, 56, v0
	v_lshl_add_u64 v[4:5], s[48:49], 0, v[20:21]
	v_lshlrev_b32_e32 v0, 1, v0
	v_lshl_add_u64 v[22:23], v[4:5], 0, v[0:1]
	v_and_b32_e32 v4, -2, v18
	v_ashrrev_i32_e32 v5, 31, v4
	v_and_b32_e32 v36, 15, v2
	v_lshlrev_b64 v[24:25], 10, v[4:5]
	v_lshl_add_u64 v[4:5], s[50:51], 0, v[24:25]
	v_lshlrev_b32_e32 v26, 4, v36
	v_mov_b32_e32 v27, v1
	v_lshl_add_u64 v[28:29], v[4:5], 0, v[26:27]
	global_load_dwordx4 v[4:7], v[22:23], off
	global_load_dwordx4 v[8:11], v[28:29], off
	global_load_dwordx4 v[12:15], v[28:29], off offset:1024
	s_ashr_i32 s23, s68, 1
	v_add_co_u32_e32 v32, vcc, s78, v22
	s_lshl_b32 s22, s21, 8
	s_andn2_b32 s23, s23, 31
	v_addc_co_u32_e32 v33, vcc, 0, v23, vcc
	s_add_i32 s23, s23, s22
	v_add_co_u32_e32 v22, vcc, s75, v22
	v_or_b32_e32 v158, s23, v36
	s_nop 0
	v_addc_co_u32_e32 v23, vcc, 0, v23, vcc
	v_lshrrev_b32_e32 v30, 5, v2
	v_ashrrev_i32_e32 v159, 31, v158
	v_or_b32_e32 v156, 16, v158
	global_load_dwordx4 v[110:113], v[32:33], off
	v_add_co_u32_e32 v32, vcc, s78, v28
	v_and_b32_e32 v40, 4, v30
	v_lshlrev_b64 v[30:31], 10, v[158:159]
	v_ashrrev_i32_e32 v157, 31, v156
	v_addc_co_u32_e32 v33, vcc, 0, v29, vcc
	v_lshl_add_u64 v[30:31], v[16:17], 0, v[30:31]
	v_lshlrev_b64 v[34:35], 10, v[156:157]
	v_add_co_u32_e32 v28, vcc, s75, v28
	global_load_dwordx4 v[82:85], v[30:31], off
	global_load_dwordx4 v[78:81], v[30:31], off offset:64
	v_addc_co_u32_e32 v29, vcc, 0, v29, vcc
	v_lshl_add_u64 v[16:17], v[16:17], 0, v[34:35]
	global_load_dwordx4 v[102:105], v[32:33], off
	global_load_dwordx4 v[106:109], v[32:33], off offset:1024
	global_load_dwordx4 v[90:93], v[22:23], off
	global_load_dwordx4 v[94:97], v[28:29], off
	global_load_dwordx4 v[98:101], v[28:29], off offset:1024
	global_load_dwordx4 v[86:89], v[16:17], off
	global_load_dwordx4 v[74:77], v[16:17], off offset:64
	v_lshlrev_b32_e32 v19, 2, v2
	v_lshrrev_b32_e32 v27, 2, v2
	v_add_u32_e32 v38, 0, v19
	v_and_b32_e32 v27, 24, v27
	v_and_b32_e32 v41, 2, v18
	s_waitcnt vmcnt(13)
	ds_write_b32 v38, v3 offset:55296
	v_and_or_b32 v3, v18, 32, v27
	s_movk_i32 s26, 0x48
	v_and_b32_e32 v16, 56, v19
	v_or3_b32 v3, v3, v40, v41
	v_mul_lo_u32 v39, v18, s26
	v_add_u32_e32 v3, v3, v16
	v_lshlrev_b32_e32 v171, 1, v39
	v_and_b32_e32 v3, 62, v3
	v_mul_u32_u24_e32 v170, 0x480, v36
	v_add3_u32 v17, 0, v171, v0
	v_lshlrev_b32_e32 v172, 1, v3
	v_add3_u32 v3, 0, v170, v172
	v_add_u32_e32 v3, 0x2400, v3
	v_lshlrev_b32_e32 v169, 3, v37
	v_lshlrev_b32_e32 v165, 2, v37
	v_and_b32_e32 v2, 7, v2
	v_or_b32_e32 v24, v24, v26
	v_lshl_or_b32 v20, v2, 4, v20
	v_sub_u32_e32 v2, v158, v165
	s_lshl_b32 s21, s21, 2
	s_sub_i32 s71, s23, 63
	v_mul_u32_u24_e32 v173, 0x90, v36
	v_mad_u32_u24 v174, v36, s80, 0
	v_lshl_add_u64 v[160:161], s[56:57], 0, v[24:25]
	v_lshl_add_u64 v[162:163], s[58:59], 0, v[20:21]
	v_lshl_add_u32 v176, v2, 2, s93
	s_mov_b32 s68, 3
	s_mov_b32 s69, 0
	s_add_i32 s70, s21, 4
	s_or_b32 s76, s23, 31
	s_sub_i32 s79, 0, s21
	v_mov_b32_e32 v175, 0
	s_mov_b32 s81, s71
	v_mov_b32_e32 v177, 0
	s_waitcnt vmcnt(12)
	ds_write_b128 v17, v[4:7]
	s_waitcnt vmcnt(11)
	v_and_b32_e32 v4, 0xffff, v8
	v_lshrrev_b32_e32 v5, 16, v8
	s_waitcnt vmcnt(10)
	v_lshl_or_b32 v4, v12, 16, v4
	v_and_or_b32 v5, v12, s33, v5
	ds_write2_b32 v3, v4, v5 offset1:36
	v_and_b32_e32 v4, 0xffff, v9
	v_lshrrev_b32_e32 v5, 16, v9
	v_lshl_or_b32 v4, v13, 16, v4
	v_and_or_b32 v5, v13, s33, v5
	ds_write2_b32 v3, v4, v5 offset0:72 offset1:108
	v_and_b32_e32 v4, 0xffff, v10
	v_lshrrev_b32_e32 v5, 16, v10
	v_lshl_or_b32 v4, v14, 16, v4
	v_and_or_b32 v5, v14, s33, v5
	ds_write2_b32 v3, v4, v5 offset0:144 offset1:180
	v_and_b32_e32 v4, 0xffff, v11
	v_lshrrev_b32_e32 v5, 16, v11
	v_lshl_or_b32 v4, v15, 16, v4
	v_and_or_b32 v5, v15, s33, v5
	ds_write2_b32 v3, v4, v5 offset0:216 offset1:252
	v_add_u32_e32 v3, 40, v169
	v_and_b32_e32 v168, 56, v3
	v_add_u32_e32 v3, 48, v169
	v_and_b32_e32 v167, 56, v3
	v_add_u32_e32 v3, 56, v169
	v_mov_b32_e32 v10, v1
	v_mov_b32_e32 v11, v1
	v_mov_b32_e32 v12, v1
	v_mov_b32_e32 v13, v1
	v_and_b32_e32 v166, 56, v3
	v_mov_b64_e32 v[24:25], v[12:13]
	v_mov_b64_e32 v[28:29], v[12:13]
	v_mov_b64_e32 v[32:33], v[12:13]
	v_mov_b64_e32 v[36:37], v[12:13]
	v_mov_b64_e32 v[44:45], v[12:13]
	v_mov_b64_e32 v[48:49], v[12:13]
	v_mov_b64_e32 v[52:53], v[12:13]
	v_mov_b64_e32 v[56:57], v[12:13]
	v_mov_b64_e32 v[60:61], v[12:13]
	v_mov_b64_e32 v[64:65], v[12:13]
	v_mov_b64_e32 v[68:69], v[12:13]
	v_mov_b64_e32 v[20:21], v[12:13]
	v_mov_b64_e32 v[16:17], v[12:13]
	v_mov_b64_e32 v[6:7], v[10:11]
	v_mov_b64_e32 v[2:3], v[10:11]
	v_mov_b64_e32 v[72:73], v[12:13]
	v_mov_b64_e32 v[40:41], v[12:13]
	v_mov_b64_e32 v[22:23], v[10:11]
	v_mov_b64_e32 v[26:27], v[10:11]
	v_mov_b64_e32 v[30:31], v[10:11]
	v_mov_b64_e32 v[34:35], v[10:11]
	v_mov_b64_e32 v[42:43], v[10:11]
	v_mov_b64_e32 v[46:47], v[10:11]
	v_mov_b64_e32 v[50:51], v[10:11]
	v_mov_b64_e32 v[54:55], v[10:11]
	v_mov_b64_e32 v[58:59], v[10:11]
	v_mov_b64_e32 v[62:63], v[10:11]
	v_mov_b64_e32 v[66:67], v[10:11]
	v_mov_b64_e32 v[18:19], v[10:11]
	v_mov_b64_e32 v[14:15], v[10:11]
	v_mov_b64_e32 v[8:9], v[12:13]
	v_mov_b64_e32 v[4:5], v[12:13]
	v_mov_b64_e32 v[70:71], v[10:11]
	v_mov_b64_e32 v[38:39], v[10:11]
	s_waitcnt vmcnt(0) lgkmcnt(0)
	s_barrier
	s_mov_b32 s95, 0
	s_cmp_gt_i32 s69, s76
	s_cbranch_scc1 .LBB0_196
	s_branch .LBB0_183

; __device__ __forceinline__ void unit(unsigned char* ws, LAS unsigned char* lds, int b, int h, int mp, int qb, const int tid_in) {
;     ...
;         if (kt + 1 < NT) { FA3_STAGE((kt + 1) & 1); kA = kB; vA0 = vB0; vA1 = vB1;
;             if (kt + 3 < NT) { const size_t off = (size_t)(kt + 3) * 64 * 512; kB = *(const u32x4*)(kg + off); vB0 = *(const u32x4*)(vg + off); vB1 = *(const u32x4*)(vg + off + 512); } }
.LBB0_183:
	s_cmpk_gt_i32 s81, 0x70
	s_cbranch_scc1 .Lattn_fast
	s_cmp_eq_u32 s95, 1
	s_cbranch_scc0 .Lattn_bd_g
	s_mov_b32 s95, 0
	s_waitcnt vmcnt(0)
	v_mov_b64_e32 v[110:111], v[90:91]
	v_mov_b64_e32 v[112:113], v[92:93]
	v_mov_b64_e32 v[102:103], v[94:95]
	v_mov_b64_e32 v[104:105], v[96:97]
	v_mov_b64_e32 v[106:107], v[98:99]
	v_mov_b64_e32 v[108:109], v[100:101]
	s_cmp_gt_u32 s68, s70
	s_cbranch_scc1 .Lattn_bn_g
	v_lshl_add_u64 v[114:115], v[160:161], 0, s[14:15]
	v_add_co_u32_e32 v114, vcc, 0xa630000, v114
	v_lshl_add_u64 v[116:117], v[162:163], 0, s[14:15]
	s_nop 0
	v_addc_co_u32_e32 v115, vcc, 0, v115, vcc
	global_load_dwordx4 v[90:93], v[116:117], off
	global_load_dwordx4 v[94:97], v[114:115], off
	global_load_dwordx4 v[98:101], v[114:115], off offset:1024
.Lattn_bn_g:
	v_lshl_add_u64 v[160:161], v[160:161], 0, s[40:41]
	v_lshl_add_u64 v[162:163], v[162:163], 0, s[40:41]

; __device__ __forceinline__ void unit(unsigned char* ws, LAS unsigned char* lds, int b, int h, int mp, int qb, const int tid_in) {
;     ...
;         if (kt + 1 < NT) { FA3_STAGE((kt + 1) & 1); kA = kB; vA0 = vB0; vA1 = vB1;
;             if (kt + 3 < NT) { const size_t off = (size_t)(kt + 3) * 64 * 512; kB = *(const u32x4*)(kg + off); vB0 = *(const u32x4*)(vg + off); vB1 = *(const u32x4*)(vg + off + 512); } }
.Lattn_b_skip:
	s_cmp_eq_u32 s95, 1
	s_cbranch_scc0 .Lattn_bd_s
	s_mov_b32 s95, 0
	s_waitcnt vmcnt(0)
	v_mov_b64_e32 v[110:111], v[90:91]
	v_mov_b64_e32 v[112:113], v[92:93]
	v_mov_b64_e32 v[102:103], v[94:95]
	v_mov_b64_e32 v[104:105], v[96:97]
	v_mov_b64_e32 v[106:107], v[98:99]
	v_mov_b64_e32 v[108:109], v[100:101]
	s_cmp_gt_u32 s68, s70
	s_cbranch_scc1 .Lattn_bn_s
	v_lshl_add_u64 v[114:115], v[160:161], 0, s[14:15]
	v_add_co_u32_e32 v114, vcc, 0xa630000, v114
	v_lshl_add_u64 v[116:117], v[162:163], 0, s[14:15]
	s_nop 0
	v_addc_co_u32_e32 v115, vcc, 0, v115, vcc
	global_load_dwordx4 v[90:93], v[116:117], off
	global_load_dwordx4 v[94:97], v[114:115], off
	global_load_dwordx4 v[98:101], v[114:115], off offset:1024

; #define LAS __attribute__((address_space(3)))
; __device__ __forceinline__ void unit(unsigned char* ws, LAS unsigned char* lds, int b, int h, int mp, int qb, const int tid_in) {
;     ...
;         for (int jt = 0; jt < 4; ++jt) { const bf16x8 kf0 = *(const LAS bf16x8*)(KS + (16 * jt + fr) * KP + 8 * fq), kf1 = *(const LAS bf16x8*)(KS + (16 * jt + fr) * KP + 32 + 8 * fq);
; #pragma unroll
;             for (int g = 0; g < 2; ++g) { const float nm = -m[g]; s[g][jt] = __builtin_amdgcn_mfma_f32_16x16x32_bf16(kf0, qf[g][0], (f32x4){nm, nm, nm, nm}, 0, 0, 0); s[g][jt] = __builtin_amdgcn_mfma_f32_16x16x32_bf16(kf1, qf[g][1], s[g][jt], 0, 0, 0); } }
;     ...
;         if (kt + 1 < NT) { FA3_STAGE((kt + 1) & 1); kA = kB; vA0 = vB0; vA1 = vB1;
;             if (kt + 3 < NT) { const size_t off = (size_t)(kt + 3) * 64 * 512; kB = *(const u32x4*)(kg + off); vB0 = *(const u32x4*)(vg + off); vB1 = *(const u32x4*)(vg + off + 512); } }
.Lattn_fast:
	s_bitcmp1_b32 s68, 0
	s_cselect_b32 s21, 0, 0x6c00
	v_add_u32_e32 v179, s21, v174
	v_lshl_add_u32 v178, v169, 1, v179
	ds_read_b128 v[222:225], v178
	ds_read_b128 v[226:229], v178 offset:64
	ds_read_b128 v[230:233], v178 offset:2304
	ds_read_b128 v[234:237], v178 offset:2368
	ds_read_b128 v[238:241], v178 offset:4608
	ds_read_b128 v[242:245], v178 offset:4672
	ds_read_b128 v[246:249], v178 offset:6912
	ds_read_b128 v[250:253], v178 offset:6976
	s_cmp_eq_u32 s95, 1
	s_cbranch_scc0 .Lattn_bd_f
	s_mov_b32 s95, 0
	s_waitcnt vmcnt(0)
	v_mov_b64_e32 v[110:111], v[90:91]
	v_mov_b64_e32 v[112:113], v[92:93]
	v_mov_b64_e32 v[102:103], v[94:95]
	v_mov_b64_e32 v[104:105], v[96:97]
	v_mov_b64_e32 v[106:107], v[98:99]
	v_mov_b64_e32 v[108:109], v[100:101]
	s_cmp_gt_u32 s68, s70
	s_cbranch_scc1 .Lattn_bn_f
	v_lshl_add_u64 v[114:115], v[160:161], 0, s[14:15]
	v_add_co_u32_e32 v114, vcc, 0xa630000, v114
	v_lshl_add_u64 v[116:117], v[162:163], 0, s[14:15]
	s_nop 0
	v_addc_co_u32_e32 v115, vcc, 0, v115, vcc
	global_load_dwordx4 v[90:93], v[116:117], off
	global_load_dwordx4 v[94:97], v[114:115], off
	global_load_dwordx4 v[98:101], v[114:115], off offset:1024

; #define LAS __attribute__((address_space(3)))
; __device__ __forceinline__ void unit(unsigned char* ws, LAS unsigned char* lds, int b, int h, int mp, int qb, const int tid_in) {
;     ...
;         for (int jt = 0; jt < 4; ++jt) { const bf16x8 kf0 = *(const LAS bf16x8*)(KS + (16 * jt + fr) * KP + 8 * fq), kf1 = *(const LAS bf16x8*)(KS + (16 * jt + fr) * KP + 32 + 8 * fq);
; #pragma unroll
;             for (int g = 0; g < 2; ++g) { const float nm = -m[g]; s[g][jt] = __builtin_amdgcn_mfma_f32_16x16x32_bf16(kf0, qf[g][0], (f32x4){nm, nm, nm, nm}, 0, 0, 0); s[g][jt] = __builtin_amdgcn_mfma_f32_16x16x32_bf16(kf1, qf[g][1], s[g][jt], 0, 0, 0); } }
;         const bool nearb = (qw0 - (k0 + 63) < 113);
;         bf16x8 pf[2][2];
; #pragma unroll
;         for (int g = 0; g < 2; ++g) {
;             if (nearb) {
;                 const LAS float* tb = TB + (256 + qw0 + 16 * g + fr - (k0 + 4 * fq));
; #pragma unroll
;                 for (int jt = 0; jt < 4; ++jt)
; #pragma unroll
;                     for (int jj = 0; jj < 4; ++jj) { const float bv = tb[-(16 * jt + jj)]; float x = s[g][jt][jj];
;                         asm("v_add_f32_e32 %0, %1, %2" : "=v"(x) : "v"(x), "v"(bv));
;                         s[g][jt][jj] = x; }
;             }
;             float mx = fmaxf(fmaxf(s[g][0][0], s[g][0][1]), fmaxf(s[g][0][2], s[g][0][3]));
; #pragma unroll
;             for (int jt = 1; jt < 4; ++jt) mx = fmaxf(mx, fmaxf(fmaxf(s[g][jt][0], s[g][jt][1]), fmaxf(s[g][jt][2], s[g][jt][3])));
;             if (__any(mx > 8.f)) {
.Lattn_bd_f:
	v_xor_b32_e32 v214, 0x80000000, v175
	v_mov_b32_e32 v215, v214
	v_mov_b32_e32 v216, v214
	v_mov_b32_e32 v217, v214
	v_xor_b32_e32 v218, 0x80000000, v177
	v_mov_b32_e32 v219, v218
	v_mov_b32_e32 v220, v218
	v_mov_b32_e32 v221, v218
	s_waitcnt lgkmcnt(7)
	v_mfma_f32_16x16x32_bf16 v[126:129], v[222:225], v[82:85], v[214:217]
	v_lshl_add_u32 v210, v168, 1, v179
	s_waitcnt lgkmcnt(6)
	v_mfma_f32_16x16x32_bf16 v[126:129], v[226:229], v[78:81], v[126:129]
	v_lshl_add_u32 v211, v167, 1, v179
	s_waitcnt lgkmcnt(5)
	v_mfma_f32_16x16x32_bf16 v[130:133], v[230:233], v[82:85], v[214:217]
	v_lshl_add_u32 v212, v166, 1, v179
	s_waitcnt lgkmcnt(4)
	v_mfma_f32_16x16x32_bf16 v[130:133], v[234:237], v[78:81], v[130:133]
	v_mov_b32_e32 v206, s20
	s_waitcnt lgkmcnt(3)
	v_mfma_f32_16x16x32_bf16 v[138:141], v[238:241], v[82:85], v[214:217]
	v_mov_b32_e32 v207, s20
	s_waitcnt lgkmcnt(2)
	v_mfma_f32_16x16x32_bf16 v[138:141], v[242:245], v[78:81], v[138:141]
	v_mov_b32_e32 v208, s20
	s_waitcnt lgkmcnt(1)
	v_mfma_f32_16x16x32_bf16 v[142:145], v[246:249], v[82:85], v[214:217]
	v_mov_b32_e32 v209, s20
	s_waitcnt lgkmcnt(0)
	v_mfma_f32_16x16x32_bf16 v[142:145], v[250:253], v[78:81], v[142:145]
	v_mfma_f32_16x16x32_bf16 v[114:117], v[222:225], v[86:89], v[218:221]
	v_mfma_f32_16x16x32_bf16 v[114:117], v[226:229], v[74:77], v[114:117]
	v_max3_f32 v181, v126, v127, v128
	v_mfma_f32_16x16x32_bf16 v[118:121], v[230:233], v[86:89], v[218:221]
	v_max3_f32 v182, v129, v130, v131
	v_mfma_f32_16x16x32_bf16 v[118:121], v[234:237], v[74:77], v[118:121]
	v_max3_f32 v181, v132, v133, v181
	v_mfma_f32_16x16x32_bf16 v[122:125], v[238:241], v[86:89], v[218:221]
	v_max3_f32 v183, v138, v139, v140
	v_mfma_f32_16x16x32_bf16 v[122:125], v[242:245], v[74:77], v[122:125]
	v_max3_f32 v181, v141, v182, v181
	v_mfma_f32_16x16x32_bf16 v[134:137], v[246:249], v[86:89], v[218:221]
	v_mfma_f32_16x16x32_bf16 v[134:137], v[250:253], v[74:77], v[134:137]
	v_max3_f32 v182, v142, v143, v144
	v_max3_f32 v181, v145, v183, v181
	v_max_f32_e32 v180, v182, v181
	v_cmp_lt_f32_e32 vcc, s94, v180
	s_cbranch_vccnz .Lattn_rare0

; __device__ __forceinline__ void unit(unsigned char* ws, LAS unsigned char* lds, int b, int h, int mp, int qb, const int tid_in) {
;     ...
;         if (kt + 1 < NT) { FA3_STAGE((kt + 1) & 1); kA = kB; vA0 = vB0; vA1 = vB1;
;             if (kt + 3 < NT) { const size_t off = (size_t)(kt + 3) * 64 * 512; kB = *(const u32x4*)(kg + off); vB0 = *(const u32x4*)(vg + off); vB1 = *(const u32x4*)(vg + off + 512); } }
;         __syncthreads();
.Lattn_stage_b:
	s_mov_b32 s95, 1
.LBB0_198:
	s_add_i32 s68, s68, 1
	s_add_i32 s21, s79, s68
	s_sub_i32 s81, s81, 64
	s_add_i32 s69, s69, 64
	s_cmp_eq_u32 s21, 6
	v_add_u32_e32 v176, 0xffffff00, v176
	s_waitcnt lgkmcnt(0)
	s_barrier
	s_cbranch_scc0 .LBB0_182
	s_cmp_eq_u32 s95, 1
	s_cbranch_scc0 .Lattn_bd_e
	s_mov_b32 s95, 0
	s_waitcnt vmcnt(0)
	v_mov_b64_e32 v[110:111], v[90:91]
	v_mov_b64_e32 v[112:113], v[92:93]
	v_mov_b64_e32 v[102:103], v[94:95]
	v_mov_b64_e32 v[104:105], v[96:97]
	v_mov_b64_e32 v[106:107], v[98:99]
	v_mov_b64_e32 v[108:109], v[100:101]
	s_cmp_gt_u32 s68, s70
	s_cbranch_scc1 .Lattn_bn_e
	v_lshl_add_u64 v[114:115], v[160:161], 0, s[14:15]
	v_add_co_u32_e32 v114, vcc, 0xa630000, v114
	v_lshl_add_u64 v[116:117], v[162:163], 0, s[14:15]
	s_nop 0
	v_addc_co_u32_e32 v115, vcc, 0, v115, vcc
	global_load_dwordx4 v[90:93], v[116:117], off
	global_load_dwordx4 v[94:97], v[114:115], off
	global_load_dwordx4 v[98:101], v[114:115], off offset:1024

; #define LAS __attribute__((address_space(3)))
; __device__ __forceinline__ void unit(unsigned char* ws, LAS unsigned char* lds, int b, int h, int mp, int qb, const int tid_in) {
;     ...
;     for (int kt = 0; kt < NT; ++kt) {
;         LAS bf16_t* KS = KV0 + (kt & 1) * KVB; LAS bf16_t* VT = KS + 64 * KP;
;         const int k0 = kt * 64;
;         if (k0 <= qw0 + 31) {
;         f32x4 s[2][4];
; #pragma unroll
;         for (int jt = 0; jt < 4; ++jt) { const bf16x8 kf0 = *(const LAS bf16x8*)(KS + (16 * jt + fr) * KP + 8 * fq), kf1 = *(const LAS bf16x8*)(KS + (16 * jt + fr) * KP + 32 + 8 * fq);
; #pragma unroll
;             for (int g = 0; g < 2; ++g) { const float nm = -m[g]; s[g][jt] = __builtin_amdgcn_mfma_f32_16x16x32_bf16(kf0, qf[g][0], (f32x4){nm, nm, nm, nm}, 0, 0, 0); s[g][jt] = __builtin_amdgcn_mfma_f32_16x16x32_bf16(kf1, qf[g][1], s[g][jt], 0, 0, 0); } }
.Lattn_bd_e:
	s_lshl_b32 s21, s68, 6
	s_addk_i32 s21, 0xff40
	s_cmp_gt_i32 s21, s76
	s_cbranch_scc1 .LBB0_171
	s_waitcnt vmcnt(2)
	v_add_u32_e32 v114, s22, v173
	v_lshl_add_u32 v0, v169, 1, v114
	ds_read_b128 v[90:93], v0
	ds_read_b128 v[98:101], v0 offset:64
	v_xor_b32_e32 v116, 0x80000000, v175
	v_mov_b32_e32 v117, v116
	s_waitcnt vmcnt(0)
	v_mov_b32_e32 v118, v116
	v_mov_b32_e32 v119, v116
	v_xor_b32_e32 v120, 0x80000000, v177
	v_mov_b32_e32 v121, v120
	v_mov_b32_e32 v122, v120
	s_waitcnt lgkmcnt(1)
	v_mfma_f32_16x16x32_bf16 v[94:97], v[90:93], v[82:85], v[116:119]
	v_mov_b32_e32 v123, v120
	s_sub_i32 s26, s71, s21
	s_cmpk_gt_i32 s26, 0x70
	s_waitcnt lgkmcnt(0)
	v_mfma_f32_16x16x32_bf16 v[102:105], v[98:101], v[78:81], v[94:97]
	ds_read_b128 v[110:113], v0 offset:2368
	s_cselect_b64 s[22:23], -1, 0
	s_cmpk_lt_i32 s26, 0x71
	ds_read_b128 v[94:97], v0 offset:2304
	v_mfma_f32_16x16x32_bf16 v[90:93], v[90:93], v[86:89], v[120:123]
	s_mov_b64 s[60:61], -1
	ds_read_b128 v[124:127], v0 offset:4672
	v_mfma_f32_16x16x32_bf16 v[90:93], v[98:101], v[74:77], v[90:93]
	s_waitcnt lgkmcnt(1)
	v_mfma_f32_16x16x32_bf16 v[98:101], v[94:97], v[82:85], v[116:119]
	v_mfma_f32_16x16x32_bf16 v[106:109], v[110:113], v[78:81], v[98:101]
	v_mfma_f32_16x16x32_bf16 v[94:97], v[94:97], v[86:89], v[120:123]
	s_nop 5
	ds_read_b128 v[98:101], v0 offset:4608
	v_mfma_f32_16x16x32_bf16 v[94:97], v[110:113], v[74:77], v[94:97]
	s_waitcnt lgkmcnt(0)
	v_mfma_f32_16x16x32_bf16 v[110:113], v[98:101], v[82:85], v[116:119]
	v_mfma_f32_16x16x32_bf16 v[98:101], v[98:101], v[86:89], v[120:123]
	v_mfma_f32_16x16x32_bf16 v[110:113], v[124:127], v[78:81], v[110:113]
	v_mfma_f32_16x16x32_bf16 v[98:101], v[124:127], v[74:77], v[98:101]
	ds_read_b128 v[124:127], v0 offset:6912
	s_waitcnt lgkmcnt(0)
	v_mfma_f32_16x16x32_bf16 v[82:85], v[124:127], v[82:85], v[116:119]
	s_nop 2
	ds_read_b128 v[116:119], v0 offset:6976
	s_waitcnt lgkmcnt(0)
	v_mfma_f32_16x16x32_bf16 v[78:81], v[116:119], v[78:81], v[82:85]
	v_mfma_f32_16x16x32_bf16 v[82:85], v[124:127], v[86:89], v[120:123]
	v_mfma_f32_16x16x32_bf16 v[74:77], v[116:119], v[74:77], v[82:85]
	s_cbranch_scc1 .LBB0_202
	s_mov_b64 s[60:61], 0
